# attention k-tile loops (MLA x2, SWA): K-fragment LDS reads issued ahead through a ring of 8 quads instead of read-wait-MFMA
# speedup vs baseline: 1.0678x; 1.0001x over previous
; #define MFMA(a, b, c) __builtin_amdgcn_mfma_f32_32x32x16_bf16((a), (b), (c), 0, 0, 0)
; template <int DQK, bool SWA> ...
;     ...
;     for (int mt = 0; mt < 2; ++mt) {
; #pragma unroll
;       for (int i = 0; i < 16; ++i) s[mt][i] = 0.f;
;       const u16* kb = Ks + buf * 64 * KSTR + (mt * 32 + r) * KSTR + hh * 8;
; #pragma unroll
;       for (int ks = 0; ks < NKS; ++ks) {
;         const bf16x8 a = *(const bf16x8*)(kb + ks * 16);
;         s[mt] = MFMA(a, bq[ks], s[mt]);
;       }
;     }
;     if (SWA && it >= 4) {
;       const int kpos0 = (kt_lo + it - 4) * 64;
;       const int qpos = qpos0 + wave * 32 + r;
; #pragma unroll
;       for (int mt = 0; mt < 2; ++mt)
; #pragma unroll
;         for (int i = 0; i < 16; ++i) {
;           const int kpos = kpos0 + mt * 32 + (i & 3) + 8 * (i >> 2) + 4 * hh;
;           const int dlt = kpos - qpos;
;           if (dlt > 128 || dlt < -128) s[mt][i] = -INFINITY;
;         }
;     }
.LBB0_775:
	s_and_b32 s4, s42, 1
	s_mul_i32 s5, s4, 0x2400
	v_add_u32_e32 v153, s5, v128
	ds_read_b128 v[224:227], v153
	ds_read_b128 v[228:231], v153 offset:32
	ds_read_b128 v[232:235], v153 offset:64
	ds_read_b128 v[236:239], v153 offset:96
	ds_read_b128 v[240:243], v153 offset:4608
	ds_read_b128 v[244:247], v153 offset:4640
	ds_read_b128 v[248:251], v153 offset:4672
	ds_read_b128 v[252:255], v153 offset:4704
	s_cmp_lt_u32 s42, 4
	s_waitcnt lgkmcnt(7)
	v_mfma_f32_32x32x16_bf16 v[48:63], v[224:227], v[64:67], 0
	s_waitcnt lgkmcnt(6)
	v_mfma_f32_32x32x16_bf16 v[48:63], v[228:231], v[68:71], v[48:63]
	s_waitcnt lgkmcnt(5)
	v_mfma_f32_32x32x16_bf16 v[48:63], v[232:235], v[72:75], v[48:63]
	s_waitcnt lgkmcnt(4)
	v_mfma_f32_32x32x16_bf16 v[48:63], v[236:239], v[76:79], v[48:63]
	s_waitcnt lgkmcnt(3)
	v_mfma_f32_32x32x16_bf16 v[32:47], v[240:243], v[64:67], 0
	s_waitcnt lgkmcnt(2)
	v_mfma_f32_32x32x16_bf16 v[32:47], v[244:247], v[68:71], v[32:47]
	s_waitcnt lgkmcnt(1)
	v_mfma_f32_32x32x16_bf16 v[32:47], v[248:251], v[72:75], v[32:47]
	s_waitcnt lgkmcnt(0)
	v_mfma_f32_32x32x16_bf16 v[32:47], v[252:255], v[76:79], v[32:47]
	s_cbranch_scc1 .LBB0_777
	v_add_u32_e32 v153, s38, v130
	v_add_u32_e32 v155, 0xfffffe7f, v153
	s_movk_i32 s42, 0xfeff
	v_cmp_gt_u32_e32 vcc, s42, v155
	v_add_u32_e32 v155, 0xfffffe80, v153
	s_nop 0
	v_cndmask_b32_e32 v48, v48, v149, vcc
	v_cmp_lt_u32_e32 vcc, s47, v155
	v_add_u32_e32 v155, 0xfffffe81, v153
	s_nop 0
	v_cndmask_b32_e32 v49, v149, v49, vcc
	v_cmp_lt_u32_e32 vcc, s47, v155
	v_add_u32_e32 v155, 0xfffffe82, v153
	s_nop 0
	v_cndmask_b32_e32 v50, v149, v50, vcc
	v_cmp_lt_u32_e32 vcc, s47, v155
	v_add_u32_e32 v155, 0xfffffe87, v153
	s_nop 0
	v_cndmask_b32_e32 v51, v149, v51, vcc
	v_cmp_lt_u32_e32 vcc, s47, v155
	v_add_u32_e32 v155, 0xfffffe88, v153
	s_nop 0
	v_cndmask_b32_e32 v52, v149, v52, vcc
	v_cmp_lt_u32_e32 vcc, s47, v155
	v_add_u32_e32 v155, 0xfffffe89, v153
	s_nop 0
	v_cndmask_b32_e32 v53, v149, v53, vcc
	v_cmp_lt_u32_e32 vcc, s47, v155
	v_add_u32_e32 v155, 0xfffffe8a, v153
	s_nop 0
	v_cndmask_b32_e32 v54, v149, v54, vcc
	v_cmp_lt_u32_e32 vcc, s47, v155
	v_add_u32_e32 v155, 0xfffffe8f, v153
	s_nop 0
	v_cndmask_b32_e32 v55, v149, v55, vcc
	v_cmp_lt_u32_e32 vcc, s47, v155
	v_add_u32_e32 v155, 0xfffffe90, v153
	s_nop 0
	v_cndmask_b32_e32 v56, v149, v56, vcc
	v_cmp_lt_u32_e32 vcc, s47, v155
	v_add_u32_e32 v155, 0xfffffe91, v153
	s_nop 0
	v_cndmask_b32_e32 v57, v149, v57, vcc
	v_cmp_lt_u32_e32 vcc, s47, v155
	v_add_u32_e32 v155, 0xfffffe92, v153
	s_nop 0
	v_cndmask_b32_e32 v58, v149, v58, vcc
	v_cmp_lt_u32_e32 vcc, s47, v155
	v_add_u32_e32 v155, 0xfffffe97, v153
	s_nop 0
	v_cndmask_b32_e32 v59, v149, v59, vcc
	v_cmp_lt_u32_e32 vcc, s47, v155
	v_add_u32_e32 v155, 0xfffffe98, v153
	s_nop 0
	v_cndmask_b32_e32 v60, v149, v60, vcc
	v_cmp_lt_u32_e32 vcc, s47, v155
	v_add_u32_e32 v155, 0xfffffe99, v153
	s_nop 0
	v_cndmask_b32_e32 v61, v149, v61, vcc
	v_cmp_lt_u32_e32 vcc, s47, v155
	v_add_u32_e32 v155, 0xfffffe9a, v153
	s_nop 0
	v_cndmask_b32_e32 v62, v149, v62, vcc
	v_cmp_lt_u32_e32 vcc, s47, v155
	v_add_u32_e32 v155, 0xfffffe9f, v153
	s_nop 0
	v_cndmask_b32_e32 v63, v149, v63, vcc
	v_cmp_lt_u32_e32 vcc, s47, v155
	v_add_u32_e32 v155, 0xfffffea0, v153
	s_nop 0
	v_cndmask_b32_e32 v32, v149, v32, vcc
	v_cmp_lt_u32_e32 vcc, s47, v155
	v_add_u32_e32 v155, 0xfffffea1, v153
	s_nop 0
	v_cndmask_b32_e32 v33, v149, v33, vcc
	v_cmp_lt_u32_e32 vcc, s47, v155
	v_add_u32_e32 v155, 0xfffffea2, v153
	s_nop 0
	v_cndmask_b32_e32 v34, v149, v34, vcc
	v_cmp_lt_u32_e32 vcc, s47, v155
	v_add_u32_e32 v155, 0xfffffea7, v153
	s_nop 0
	v_cndmask_b32_e32 v35, v149, v35, vcc
	v_cmp_lt_u32_e32 vcc, s47, v155
	v_add_u32_e32 v155, 0xfffffea8, v153
	s_nop 0
	v_cndmask_b32_e32 v36, v149, v36, vcc
	v_cmp_lt_u32_e32 vcc, s47, v155
	v_add_u32_e32 v155, 0xfffffea9, v153
	s_nop 0
	v_cndmask_b32_e32 v37, v149, v37, vcc
	v_cmp_lt_u32_e32 vcc, s47, v155
	v_add_u32_e32 v155, 0xfffffeaa, v153
	s_nop 0
	v_cndmask_b32_e32 v38, v149, v38, vcc
	v_cmp_lt_u32_e32 vcc, s47, v155
	v_add_u32_e32 v155, 0xfffffeaf, v153
	s_nop 0
	v_cndmask_b32_e32 v39, v149, v39, vcc
	v_cmp_lt_u32_e32 vcc, s47, v155
	v_add_u32_e32 v155, 0xfffffeb0, v153
	s_nop 0
	v_cndmask_b32_e32 v40, v149, v40, vcc
	v_cmp_lt_u32_e32 vcc, s47, v155
	v_add_u32_e32 v155, 0xfffffeb1, v153
	s_nop 0
	v_cndmask_b32_e32 v41, v149, v41, vcc
	v_cmp_lt_u32_e32 vcc, s47, v155
	v_add_u32_e32 v155, 0xfffffeb2, v153
	s_nop 0
	v_cndmask_b32_e32 v42, v149, v42, vcc
	v_cmp_lt_u32_e32 vcc, s47, v155
	v_add_u32_e32 v155, 0xfffffeb7, v153
	s_nop 0
	v_cndmask_b32_e32 v43, v149, v43, vcc
	v_cmp_lt_u32_e32 vcc, s47, v155
	v_add_u32_e32 v155, 0xfffffeb8, v153
	s_nop 0
	v_cndmask_b32_e32 v44, v149, v44, vcc
	v_cmp_lt_u32_e32 vcc, s47, v155
	v_add_u32_e32 v155, 0xfffffeb9, v153
	v_add_u32_e32 v153, 0xfffffeba, v153
	v_cndmask_b32_e32 v45, v149, v45, vcc
	v_cmp_lt_u32_e32 vcc, s47, v155
	s_nop 1
	v_cndmask_b32_e32 v46, v149, v46, vcc
	v_cmp_lt_u32_e32 vcc, s47, v153
	s_nop 1
	v_cndmask_b32_e32 v47, v149, v47, vcc

; template <int DQK, bool SWA> ...
;     ...
;     for (int mt = 0; mt < 2; ++mt) {
; #pragma unroll
;       for (int i = 0; i < 16; ++i) s[mt][i] = 0.f;
;       const u16* kb = Ks + buf * 64 * KSTR + (mt * 32 + r) * KSTR + hh * 8;
; #pragma unroll
;       for (int ks = 0; ks < NKS; ++ks) {
;         const bf16x8 a = *(const bf16x8*)(kb + ks * 16);
;         s[mt] = MFMA(a, bq[ks], s[mt]);
;       }
;     }
;     if (SWA && it >= 4) {
;       const int kpos0 = (kt_lo + it - 4) * 64;
;       const int qpos = qpos0 + wave * 32 + r;
; #pragma unroll
;       for (int mt = 0; mt < 2; ++mt)
; #pragma unroll
;         for (int i = 0; i < 16; ++i) {
;           const int kpos = kpos0 + mt * 32 + (i & 3) + 8 * (i >> 2) + 4 * hh;
;           const int dlt = kpos - qpos;
;           if (dlt > 128 || dlt < -128) s[mt][i] = -INFINITY;
;         }
;     }
;     float mx = -INFINITY;
; #pragma unroll
;     for (int mt = 0; mt < 2; ++mt)
; #pragma unroll
;       for (int i = 0; i < 16; ++i) mx = fmaxf(mx, s[mt][i]);
;     mx = fmaxf(mx, __shfl_xor(mx, 32));
;     const float mnew = fmaxf(m, mx);
;     const float alpha = __builtin_amdgcn_exp2f(m - mnew);
;     m = mnew;
;     float psum = 0.f;
; #pragma unroll
;     for (int mt = 0; mt < 2; ++mt)
; #pragma unroll
;       for (int i = 0; i < 16; ++i) {
;         const float pv = __builtin_amdgcn_exp2f(s[mt][i] - mnew);
;         s[mt][i] = pv;
;         psum += pv;
;       }
;     lsum = lsum * alpha + psum;
; #pragma unroll
;     for (int a = 0; a < 2; ++a)
; #pragma unroll
;       for (int i = 0; i < 16; ++i) o[a][i] *= alpha;
; #pragma unroll
;     for (int mt = 0; mt < 2; ++mt)
; #pragma unroll
;       for (int sx = 0; sx < 2; ++sx) {
;         uint4 pu;
;         pu.x = pack2(s[mt][8 * sx + 0], s[mt][8 * sx + 1]);
;         pu.y = pack2(s[mt][8 * sx + 2], s[mt][8 * sx + 3]);
;         pu.z = pack2(s[mt][8 * sx + 4], s[mt][8 * sx + 5]);
;         pu.w = pack2(s[mt][8 * sx + 6], s[mt][8 * sx + 7]);
;         const bf16x8 pfv = __builtin_bit_cast(bf16x8, pu);
; #pragma unroll
;         for (int dt = 0; dt < 2; ++dt) {
;           const u16* vp = Vt + buf * 64 * VSTR + (dt * 32 + r) * VSTR + mt * 32 + 16 * sx + 4 * hh;
;           const uint2 v0 = *(const uint2*)(vp);
;           const uint2 v1 = *(const uint2*)(vp + 8);
;           const uint4 vu = make_uint4(v0.x, v0.y, v1.x, v1.y);
.LBB0_1184:
	s_and_b32 s18, s17, 1
	s_mul_i32 s19, s18, 0x3400
	v_add3_u32 v171, v160, s19, v163
	ds_read_b128 v[224:227], v171
	ds_read_b128 v[228:231], v171 offset:32
	ds_read_b128 v[232:235], v171 offset:64
	ds_read_b128 v[236:239], v171 offset:96
	ds_read_b128 v[240:243], v171 offset:128
	ds_read_b128 v[244:247], v171 offset:160
	ds_read_b128 v[248:251], v171 offset:6656
	ds_read_b128 v[252:255], v171 offset:6688
	s_mul_i32 s19, s18, 0x2400
	v_add3_u32 v184, v162, s19, v164
	v_add_u32_e32 v185, 0x6800, v184
	v_add_u32_e32 v184, 0x7800, v184
	s_andn2_b64 vcc, exec, s[0:1]
	s_waitcnt lgkmcnt(7)
	v_mfma_f32_32x32x16_bf16 v[48:63], v[224:227], v[64:67], 0
	ds_read_b128 v[224:227], v171 offset:6720
	s_waitcnt lgkmcnt(7)
	v_mfma_f32_32x32x16_bf16 v[48:63], v[228:231], v[68:71], v[48:63]
	ds_read_b128 v[228:231], v171 offset:6752
	s_waitcnt lgkmcnt(7)
	v_mfma_f32_32x32x16_bf16 v[48:63], v[232:235], v[72:75], v[48:63]
	ds_read_b128 v[232:235], v171 offset:6784
	s_waitcnt lgkmcnt(7)
	v_mfma_f32_32x32x16_bf16 v[48:63], v[236:239], v[76:79], v[48:63]
	ds_read_b128 v[236:239], v171 offset:6816
	s_waitcnt lgkmcnt(7)
	v_mfma_f32_32x32x16_bf16 v[48:63], v[240:243], v[80:83], v[48:63]
	s_waitcnt lgkmcnt(6)
	v_mfma_f32_32x32x16_bf16 v[48:63], v[244:247], v[84:87], v[48:63]
	s_waitcnt lgkmcnt(5)
	v_mfma_f32_32x32x16_bf16 v[32:47], v[248:251], v[64:67], 0
	s_waitcnt lgkmcnt(4)
	v_mfma_f32_32x32x16_bf16 v[32:47], v[252:255], v[68:71], v[32:47]
	s_waitcnt lgkmcnt(3)
	v_mfma_f32_32x32x16_bf16 v[32:47], v[224:227], v[72:75], v[32:47]
	v_max3_f32 v171, v48, s22, v49
	v_max3_f32 v171, v171, v50, v51
	s_waitcnt lgkmcnt(2)
	v_mfma_f32_32x32x16_bf16 v[32:47], v[228:231], v[76:79], v[32:47]
	v_max3_f32 v171, v171, v52, v53
	v_max3_f32 v171, v171, v54, v55
	s_waitcnt lgkmcnt(1)
	v_mfma_f32_32x32x16_bf16 v[32:47], v[232:235], v[80:83], v[32:47]
	v_max3_f32 v171, v171, v56, v57
	v_max3_f32 v171, v171, v58, v59
	s_waitcnt lgkmcnt(0)
	v_mfma_f32_32x32x16_bf16 v[32:47], v[236:239], v[84:87], v[32:47]
	v_max3_f32 v171, v171, v60, v61
	v_max3_f32 v171, v171, v62, v63
	ds_read2_b64 v[176:179], v185 offset1:2
	ds_read2_b64 v[180:183], v185 offset0:4 offset1:6
	s_nop 7
	v_max3_f32 v171, v171, v32, v33
	v_max3_f32 v171, v171, v34, v35
	v_max3_f32 v171, v171, v36, v37
	v_max3_f32 v171, v171, v38, v39
	v_max3_f32 v171, v171, v40, v41
	v_max3_f32 v171, v171, v42, v43
	v_max3_f32 v171, v171, v44, v45
	v_max3_f32 v171, v171, v46, v47
	ds_bpermute_b32 v172, v161, v171
	s_waitcnt lgkmcnt(0)
	v_max3_f32 v171, v130, v171, v172
	v_sub_f32_e32 v130, v130, v171
	v_sub_f32_e32 v48, v48, v171
	v_sub_f32_e32 v49, v49, v171
	v_sub_f32_e32 v50, v50, v171
	v_sub_f32_e32 v51, v51, v171
	v_sub_f32_e32 v52, v52, v171
	v_sub_f32_e32 v53, v53, v171
	v_sub_f32_e32 v54, v54, v171
	v_sub_f32_e32 v55, v55, v171
	v_exp_f32_e32 v130, v130
	v_exp_f32_e32 v48, v48
	v_exp_f32_e32 v49, v49
	v_exp_f32_e32 v50, v50
	v_exp_f32_e32 v51, v51
	v_exp_f32_e32 v52, v52
	v_exp_f32_e32 v53, v53
	v_exp_f32_e32 v54, v54
	v_exp_f32_e32 v55, v55
	v_pk_mul_f32 v[30:31], v[30:31], v[130:131] op_sel_hi:[1,0]
	v_pk_mul_f32 v[28:29], v[28:29], v[130:131] op_sel_hi:[1,0]
	v_pk_mul_f32 v[26:27], v[26:27], v[130:131] op_sel_hi:[1,0]
	v_pk_mul_f32 v[24:25], v[24:25], v[130:131] op_sel_hi:[1,0]
	v_pk_mul_f32 v[22:23], v[22:23], v[130:131] op_sel_hi:[1,0]
	v_pk_mul_f32 v[20:21], v[20:21], v[130:131] op_sel_hi:[1,0]
	v_pk_mul_f32 v[18:19], v[18:19], v[130:131] op_sel_hi:[1,0]
	v_pk_mul_f32 v[16:17], v[16:17], v[130:131] op_sel_hi:[1,0]
	v_cvt_pk_bf16_f32 v172, v48, v49
	v_cvt_pk_bf16_f32 v173, v50, v51
	v_cvt_pk_bf16_f32 v174, v52, v53
	v_cvt_pk_bf16_f32 v175, v54, v55
	v_pk_mul_f32 v[14:15], v[14:15], v[130:131] op_sel_hi:[1,0]
	v_pk_mul_f32 v[12:13], v[12:13], v[130:131] op_sel_hi:[1,0]
	v_mfma_f32_32x32x16_bf16 v[16:31], v[176:179], v[172:175], v[16:31]
	ds_read2_b64 v[176:179], v184 offset0:64 offset1:66
	v_mul_f32_e64 v10, v10, v130
	v_mul_f32_e64 v11, v11, v130
	v_mul_f32_e64 v8, v8, v130
	v_mul_f32_e64 v9, v9, v130
	v_pk_mul_f32 v[6:7], v[6:7], v[130:131] op_sel_hi:[1,0]
	v_pk_mul_f32 v[4:5], v[4:5], v[130:131] op_sel_hi:[1,0]
	v_pk_mul_f32 v[2:3], v[2:3], v[130:131] op_sel_hi:[1,0]
	v_pk_mul_f32 v[0:1], v[0:1], v[130:131] op_sel_hi:[1,0]
	v_sub_f32_e32 v56, v56, v171
	v_sub_f32_e32 v57, v57, v171
	s_waitcnt lgkmcnt(0)
	v_mfma_f32_32x32x16_bf16 v[0:15], v[176:179], v[172:175], v[0:15]
	ds_read2_b64 v[176:179], v184 offset0:68 offset1:70
	v_sub_f32_e32 v58, v58, v171
	v_sub_f32_e32 v59, v59, v171
	v_sub_f32_e32 v60, v60, v171
	v_sub_f32_e32 v61, v61, v171
	v_sub_f32_e32 v62, v62, v171
	v_sub_f32_e32 v63, v63, v171
	v_exp_f32_e32 v56, v56
	v_exp_f32_e32 v57, v57
	v_exp_f32_e32 v58, v58
	v_exp_f32_e32 v59, v59
	v_exp_f32_e32 v60, v60
	v_exp_f32_e32 v61, v61
	v_exp_f32_e32 v62, v62
	v_exp_f32_e32 v63, v63
	v_cvt_pk_bf16_f32 v172, v56, v57
	v_cvt_pk_bf16_f32 v173, v58, v59
	v_cvt_pk_bf16_f32 v174, v60, v61
	v_cvt_pk_bf16_f32 v175, v62, v63
	v_sub_f32_e32 v32, v32, v171
	v_sub_f32_e32 v33, v33, v171
	s_waitcnt lgkmcnt(0)
	v_mfma_f32_32x32x16_bf16 v[0:15], v[176:179], v[172:175], v[0:15]
	ds_read2_b64 v[176:179], v185 offset0:8 offset1:10
	v_sub_f32_e32 v34, v34, v171
	v_sub_f32_e32 v35, v35, v171
	v_sub_f32_e32 v36, v36, v171
	v_sub_f32_e32 v37, v37, v171
	v_sub_f32_e32 v38, v38, v171
	v_sub_f32_e32 v39, v39, v171
	v_mfma_f32_32x32x16_bf16 v[16:31], v[180:183], v[172:175], v[16:31]
	v_exp_f32_e32 v32, v32
	v_exp_f32_e32 v33, v33
	v_exp_f32_e32 v34, v34
	v_exp_f32_e32 v35, v35
	v_exp_f32_e32 v36, v36
	v_exp_f32_e32 v37, v37
	v_exp_f32_e32 v38, v38
	v_exp_f32_e32 v39, v39
	v_cvt_pk_bf16_f32 v172, v32, v33
	v_cvt_pk_bf16_f32 v173, v34, v35
	v_cvt_pk_bf16_f32 v174, v36, v37
	v_cvt_pk_bf16_f32 v175, v38, v39
	v_sub_f32_e32 v40, v40, v171
	v_sub_f32_e32 v41, v41, v171
	s_waitcnt lgkmcnt(0)
	v_mfma_f32_32x32x16_bf16 v[16:31], v[176:179], v[172:175], v[16:31]
	ds_read2_b64 v[176:179], v184 offset0:72 offset1:74
	v_sub_f32_e32 v42, v42, v171
	v_sub_f32_e32 v43, v43, v171
	v_sub_f32_e32 v44, v44, v171
	v_sub_f32_e32 v45, v45, v171
	v_sub_f32_e32 v46, v46, v171
	v_sub_f32_e32 v47, v47, v171
	s_waitcnt lgkmcnt(0)
	v_mfma_f32_32x32x16_bf16 v[0:15], v[176:179], v[172:175], v[0:15]
	ds_read2_b64 v[176:179], v185 offset0:12 offset1:14
	v_exp_f32_e32 v40, v40
	v_exp_f32_e32 v41, v41
	v_exp_f32_e32 v42, v42
	v_exp_f32_e32 v43, v43
	v_exp_f32_e32 v44, v44
	v_exp_f32_e32 v45, v45
	v_exp_f32_e32 v46, v46
	v_exp_f32_e32 v47, v47
	v_cvt_pk_bf16_f32 v172, v40, v41
	v_cvt_pk_bf16_f32 v173, v42, v43
	v_cvt_pk_bf16_f32 v174, v44, v45
	v_cvt_pk_bf16_f32 v175, v46, v47
	s_waitcnt lgkmcnt(0)
	s_nop 0
	v_mfma_f32_32x32x16_bf16 v[16:31], v[176:179], v[172:175], v[16:31]
	ds_read2_b64 v[176:179], v184 offset0:76 offset1:78
	s_waitcnt lgkmcnt(0)
	v_mfma_f32_32x32x16_bf16 v[0:15], v[176:179], v[172:175], v[0:15]
	s_cbranch_vccnz .LBB0_1186
; template <int DQK, bool SWA> ...
;     ...
;     if (it + 1 < nt) A_STORES(buf ^ 1);
	s_xor_b32 s0, s18, 1
	s_mul_i32 s1, s0, 0x3400
	s_add_i32 s1, s1, 0
	v_add3_u32 v172, s1, v153, v154
	s_waitcnt vmcnt(4)
	ds_write_b128 v172, v[88:91]
	v_add3_u32 v172, s1, v155, v156
	s_waitcnt vmcnt(3)
	ds_write_b128 v172, v[92:95]
	v_add3_u32 v172, s1, v157, v158
	s_mulk_i32 s0, 0x2400
	s_waitcnt vmcnt(2)
	ds_write_b128 v172, v[98:101]
	v_add_u32_e32 v172, s0, v159
	v_lshl_add_u32 v173, v115, 1, v172
	v_lshl_add_u32 v172, v131, 1, v172
	s_waitcnt vmcnt(1)
	ds_write_b16 v173, v102 offset:26624
	ds_write_b16_d16_hi v173, v102 offset:26768
	ds_write_b16 v173, v103 offset:26912
	ds_write_b16_d16_hi v173, v103 offset:27056
	ds_write_b16 v173, v104 offset:27200
	ds_write_b16_d16_hi v173, v104 offset:27344
	ds_write_b16 v173, v105 offset:27488
	ds_write_b16_d16_hi v173, v105 offset:27632
	s_waitcnt vmcnt(0)
	ds_write_b16 v172, v106 offset:26624
	ds_write_b16_d16_hi v172, v106 offset:26768
	ds_write_b16 v172, v107 offset:26912
	ds_write_b16_d16_hi v172, v107 offset:27056
	ds_write_b16 v172, v108 offset:27200
	ds_write_b16_d16_hi v172, v108 offset:27344
	ds_write_b16 v172, v109 offset:27488
	ds_write_b16_d16_hi v172, v109 offset:27632

; template <int DQK, bool SWA> ...
;     ...
;     for (int mt = 0; mt < 2; ++mt) {
; #pragma unroll
;       for (int i = 0; i < 16; ++i) s[mt][i] = 0.f;
;       const u16* kb = Ks + buf * 64 * KSTR + (mt * 32 + r) * KSTR + hh * 8;
; #pragma unroll
;       for (int ks = 0; ks < NKS; ++ks) {
;         const bf16x8 a = *(const bf16x8*)(kb + ks * 16);
;         s[mt] = MFMA(a, bq[ks], s[mt]);
;       }
;     }
;     if (SWA && it >= 4) {
;       const int kpos0 = (kt_lo + it - 4) * 64;
;       const int qpos = qpos0 + wave * 32 + r;
; #pragma unroll
;       for (int mt = 0; mt < 2; ++mt)
; #pragma unroll
;         for (int i = 0; i < 16; ++i) {
;           const int kpos = kpos0 + mt * 32 + (i & 3) + 8 * (i >> 2) + 4 * hh;
;           const int dlt = kpos - qpos;
;           if (dlt > 128 || dlt < -128) s[mt][i] = -INFINITY;
;         }
;     }
;     float mx = -INFINITY;
; #pragma unroll
;     for (int mt = 0; mt < 2; ++mt)
; #pragma unroll
;       for (int i = 0; i < 16; ++i) mx = fmaxf(mx, s[mt][i]);
;     mx = fmaxf(mx, __shfl_xor(mx, 32));
;     const float mnew = fmaxf(m, mx);
;     const float alpha = __builtin_amdgcn_exp2f(m - mnew);
;     m = mnew;
;     float psum = 0.f;
; #pragma unroll
;     for (int mt = 0; mt < 2; ++mt)
; #pragma unroll
;       for (int i = 0; i < 16; ++i) {
;         const float pv = __builtin_amdgcn_exp2f(s[mt][i] - mnew);
;         s[mt][i] = pv;
;         psum += pv;
;       }
;     lsum = lsum * alpha + psum;
; #pragma unroll
;     for (int a = 0; a < 2; ++a)
; #pragma unroll
;       for (int i = 0; i < 16; ++i) o[a][i] *= alpha;
; #pragma unroll
;     for (int mt = 0; mt < 2; ++mt)
; #pragma unroll
;       for (int sx = 0; sx < 2; ++sx) {
;         uint4 pu;
;         pu.x = pack2(s[mt][8 * sx + 0], s[mt][8 * sx + 1]);
;         pu.y = pack2(s[mt][8 * sx + 2], s[mt][8 * sx + 3]);
;         pu.z = pack2(s[mt][8 * sx + 4], s[mt][8 * sx + 5]);
;         pu.w = pack2(s[mt][8 * sx + 6], s[mt][8 * sx + 7]);
;         const bf16x8 pfv = __builtin_bit_cast(bf16x8, pu);
; #pragma unroll
;         for (int dt = 0; dt < 2; ++dt) {
;           const u16* vp = Vt + buf * 64 * VSTR + (dt * 32 + r) * VSTR + mt * 32 + 16 * sx + 4 * hh;
;           const uint2 v0 = *(const uint2*)(vp);
;           const uint2 v1 = *(const uint2*)(vp + 8);
;           const uint4 vu = make_uint4(v0.x, v0.y, v1.x, v1.y);
.LBB0_1192:
	s_and_b32 s18, s15, 1
	s_mul_i32 s19, s18, 0x3400
	v_add3_u32 v169, v163, s19, v166
	ds_read_b128 v[224:227], v169
	ds_read_b128 v[228:231], v169 offset:32
	ds_read_b128 v[232:235], v169 offset:64
	ds_read_b128 v[236:239], v169 offset:96
	ds_read_b128 v[240:243], v169 offset:128
	ds_read_b128 v[244:247], v169 offset:160
	ds_read_b128 v[248:251], v169 offset:6656
	ds_read_b128 v[252:255], v169 offset:6688
	s_mul_i32 s19, s18, 0x2400
	v_add3_u32 v182, v165, s19, v167
	v_add_u32_e32 v183, 0x6800, v182
	v_add_u32_e32 v182, 0x7800, v182
	s_andn2_b64 vcc, exec, s[0:1]
	s_waitcnt lgkmcnt(7)
	v_mfma_f32_32x32x16_bf16 v[48:63], v[224:227], v[64:67], 0
	ds_read_b128 v[224:227], v169 offset:6720
	s_waitcnt lgkmcnt(7)
	v_mfma_f32_32x32x16_bf16 v[48:63], v[228:231], v[68:71], v[48:63]
	ds_read_b128 v[228:231], v169 offset:6752
	s_waitcnt lgkmcnt(7)
	v_mfma_f32_32x32x16_bf16 v[48:63], v[232:235], v[72:75], v[48:63]
	ds_read_b128 v[232:235], v169 offset:6784
	s_waitcnt lgkmcnt(7)
	v_mfma_f32_32x32x16_bf16 v[48:63], v[236:239], v[76:79], v[48:63]
	ds_read_b128 v[236:239], v169 offset:6816
	s_waitcnt lgkmcnt(7)
	v_mfma_f32_32x32x16_bf16 v[48:63], v[240:243], v[80:83], v[48:63]
	s_waitcnt lgkmcnt(6)
	v_mfma_f32_32x32x16_bf16 v[48:63], v[244:247], v[84:87], v[48:63]
	s_waitcnt lgkmcnt(5)
	v_mfma_f32_32x32x16_bf16 v[32:47], v[248:251], v[64:67], 0
	s_waitcnt lgkmcnt(4)
	v_mfma_f32_32x32x16_bf16 v[32:47], v[252:255], v[68:71], v[32:47]
	s_waitcnt lgkmcnt(3)
	v_mfma_f32_32x32x16_bf16 v[32:47], v[224:227], v[72:75], v[32:47]
	v_max3_f32 v169, v48, s22, v49
	v_max3_f32 v169, v169, v50, v51
	s_waitcnt lgkmcnt(2)
	v_mfma_f32_32x32x16_bf16 v[32:47], v[228:231], v[76:79], v[32:47]
	v_max3_f32 v169, v169, v52, v53
	v_max3_f32 v169, v169, v54, v55
	s_waitcnt lgkmcnt(1)
	v_mfma_f32_32x32x16_bf16 v[32:47], v[232:235], v[80:83], v[32:47]
	v_max3_f32 v169, v169, v56, v57
	v_max3_f32 v169, v169, v58, v59
	s_waitcnt lgkmcnt(0)
	v_mfma_f32_32x32x16_bf16 v[32:47], v[236:239], v[84:87], v[32:47]
	v_max3_f32 v169, v169, v60, v61
	v_max3_f32 v169, v169, v62, v63
	ds_read2_b64 v[174:177], v183 offset1:2
	ds_read2_b64 v[178:181], v183 offset0:4 offset1:6
	s_nop 7
	v_max3_f32 v169, v169, v32, v33
	v_max3_f32 v169, v169, v34, v35
	v_max3_f32 v169, v169, v36, v37
	v_max3_f32 v169, v169, v38, v39
	v_max3_f32 v169, v169, v40, v41
	v_max3_f32 v169, v169, v42, v43
	v_max3_f32 v169, v169, v44, v45
	v_max3_f32 v169, v169, v46, v47
	ds_bpermute_b32 v170, v164, v169
	s_waitcnt lgkmcnt(0)
	v_max3_f32 v169, v130, v169, v170
	v_sub_f32_e32 v130, v130, v169
	v_sub_f32_e32 v48, v48, v169
	v_sub_f32_e32 v49, v49, v169
	v_sub_f32_e32 v50, v50, v169
	v_sub_f32_e32 v51, v51, v169
	v_sub_f32_e32 v52, v52, v169
	v_sub_f32_e32 v53, v53, v169
	v_sub_f32_e32 v54, v54, v169
	v_sub_f32_e32 v55, v55, v169
	v_exp_f32_e32 v130, v130
	v_exp_f32_e32 v48, v48
	v_exp_f32_e32 v49, v49
	v_exp_f32_e32 v50, v50
	v_exp_f32_e32 v51, v51
	v_exp_f32_e32 v52, v52
	v_exp_f32_e32 v53, v53
	v_exp_f32_e32 v54, v54
	v_exp_f32_e32 v55, v55
	v_pk_mul_f32 v[30:31], v[30:31], v[130:131] op_sel_hi:[1,0]
	v_pk_mul_f32 v[28:29], v[28:29], v[130:131] op_sel_hi:[1,0]
	v_pk_mul_f32 v[26:27], v[26:27], v[130:131] op_sel_hi:[1,0]
	v_pk_mul_f32 v[24:25], v[24:25], v[130:131] op_sel_hi:[1,0]
	v_pk_mul_f32 v[22:23], v[22:23], v[130:131] op_sel_hi:[1,0]
	v_pk_mul_f32 v[20:21], v[20:21], v[130:131] op_sel_hi:[1,0]
	v_pk_mul_f32 v[18:19], v[18:19], v[130:131] op_sel_hi:[1,0]
	v_pk_mul_f32 v[16:17], v[16:17], v[130:131] op_sel_hi:[1,0]
	v_cvt_pk_bf16_f32 v170, v48, v49
	v_cvt_pk_bf16_f32 v171, v50, v51
	v_cvt_pk_bf16_f32 v172, v52, v53
	v_cvt_pk_bf16_f32 v173, v54, v55
	v_pk_mul_f32 v[14:15], v[14:15], v[130:131] op_sel_hi:[1,0]
	v_pk_mul_f32 v[12:13], v[12:13], v[130:131] op_sel_hi:[1,0]
	v_mfma_f32_32x32x16_bf16 v[16:31], v[174:177], v[170:173], v[16:31]
	ds_read2_b64 v[174:177], v182 offset0:64 offset1:66
	v_mul_f32_e64 v10, v10, v130
	v_mul_f32_e64 v11, v11, v130
	v_mul_f32_e64 v8, v8, v130
	v_mul_f32_e64 v9, v9, v130
	v_pk_mul_f32 v[6:7], v[6:7], v[130:131] op_sel_hi:[1,0]
	v_pk_mul_f32 v[4:5], v[4:5], v[130:131] op_sel_hi:[1,0]
	v_pk_mul_f32 v[2:3], v[2:3], v[130:131] op_sel_hi:[1,0]
	v_pk_mul_f32 v[0:1], v[0:1], v[130:131] op_sel_hi:[1,0]
	v_sub_f32_e32 v56, v56, v169
	v_sub_f32_e32 v57, v57, v169
	s_waitcnt lgkmcnt(0)
	v_mfma_f32_32x32x16_bf16 v[0:15], v[174:177], v[170:173], v[0:15]
	ds_read2_b64 v[174:177], v182 offset0:68 offset1:70
	v_sub_f32_e32 v58, v58, v169
	v_sub_f32_e32 v59, v59, v169
	v_sub_f32_e32 v60, v60, v169
	v_sub_f32_e32 v61, v61, v169
	v_sub_f32_e32 v62, v62, v169
	v_sub_f32_e32 v63, v63, v169
	v_exp_f32_e32 v56, v56
	v_exp_f32_e32 v57, v57
	v_exp_f32_e32 v58, v58
	v_exp_f32_e32 v59, v59
	v_exp_f32_e32 v60, v60
	v_exp_f32_e32 v61, v61
	v_exp_f32_e32 v62, v62
	v_exp_f32_e32 v63, v63
	v_cvt_pk_bf16_f32 v170, v56, v57
	v_cvt_pk_bf16_f32 v171, v58, v59
	v_cvt_pk_bf16_f32 v172, v60, v61
	v_cvt_pk_bf16_f32 v173, v62, v63
	v_sub_f32_e32 v32, v32, v169
	v_sub_f32_e32 v33, v33, v169
	s_waitcnt lgkmcnt(0)
	v_mfma_f32_32x32x16_bf16 v[0:15], v[174:177], v[170:173], v[0:15]
	ds_read2_b64 v[174:177], v183 offset0:8 offset1:10
	v_sub_f32_e32 v34, v34, v169
	v_sub_f32_e32 v35, v35, v169
	v_sub_f32_e32 v36, v36, v169
	v_sub_f32_e32 v37, v37, v169
	v_sub_f32_e32 v38, v38, v169
	v_sub_f32_e32 v39, v39, v169
	v_mfma_f32_32x32x16_bf16 v[16:31], v[178:181], v[170:173], v[16:31]
	v_exp_f32_e32 v32, v32
	v_exp_f32_e32 v33, v33
	v_exp_f32_e32 v34, v34
	v_exp_f32_e32 v35, v35
	v_exp_f32_e32 v36, v36
	v_exp_f32_e32 v37, v37
	v_exp_f32_e32 v38, v38
	v_exp_f32_e32 v39, v39
	v_cvt_pk_bf16_f32 v170, v32, v33
	v_cvt_pk_bf16_f32 v171, v34, v35
	v_cvt_pk_bf16_f32 v172, v36, v37
	v_cvt_pk_bf16_f32 v173, v38, v39
	v_sub_f32_e32 v40, v40, v169
	v_sub_f32_e32 v41, v41, v169
	s_waitcnt lgkmcnt(0)
	v_mfma_f32_32x32x16_bf16 v[16:31], v[174:177], v[170:173], v[16:31]
	ds_read2_b64 v[174:177], v182 offset0:72 offset1:74
	v_sub_f32_e32 v42, v42, v169
	v_sub_f32_e32 v43, v43, v169
	v_sub_f32_e32 v44, v44, v169
	v_sub_f32_e32 v45, v45, v169
	v_sub_f32_e32 v46, v46, v169
	v_sub_f32_e32 v47, v47, v169
	s_waitcnt lgkmcnt(0)
	v_mfma_f32_32x32x16_bf16 v[0:15], v[174:177], v[170:173], v[0:15]
	ds_read2_b64 v[174:177], v183 offset0:12 offset1:14
	v_exp_f32_e32 v40, v40
	v_exp_f32_e32 v41, v41
	v_exp_f32_e32 v42, v42
	v_exp_f32_e32 v43, v43
	v_exp_f32_e32 v44, v44
	v_exp_f32_e32 v45, v45
	v_exp_f32_e32 v46, v46
	v_exp_f32_e32 v47, v47
	v_cvt_pk_bf16_f32 v170, v40, v41
	v_cvt_pk_bf16_f32 v171, v42, v43
	v_cvt_pk_bf16_f32 v172, v44, v45
	v_cvt_pk_bf16_f32 v173, v46, v47
	s_waitcnt lgkmcnt(0)
	s_nop 0
	v_mfma_f32_32x32x16_bf16 v[16:31], v[174:177], v[170:173], v[16:31]
	ds_read2_b64 v[174:177], v182 offset0:76 offset1:78
	s_waitcnt lgkmcnt(0)
	v_mfma_f32_32x32x16_bf16 v[0:15], v[174:177], v[170:173], v[0:15]
	s_cbranch_vccnz .LBB0_1194
; template <int DQK, bool SWA> ...
;     ...
;     if (it + 1 < nt) A_STORES(buf ^ 1);
	s_xor_b32 s0, s18, 1
	s_mul_i32 s1, s0, 0x3400
	s_add_i32 s1, s1, 0
	v_add3_u32 v170, s1, v156, v157
	s_waitcnt vmcnt(4)
	ds_write_b128 v170, v[88:91]
	v_add3_u32 v170, s1, v158, v159
	s_waitcnt vmcnt(3)
	ds_write_b128 v170, v[92:95]
	v_add3_u32 v170, s1, v160, v161
	s_mulk_i32 s0, 0x2400
	s_waitcnt vmcnt(2)
	ds_write_b128 v170, v[98:101]
	v_add_u32_e32 v170, s0, v162
	v_lshl_add_u32 v171, v154, 1, v170
	v_lshl_add_u32 v170, v155, 1, v170
	s_waitcnt vmcnt(1)
	ds_write_b16 v171, v102 offset:26624
	ds_write_b16_d16_hi v171, v102 offset:26768
	ds_write_b16 v171, v103 offset:26912
	ds_write_b16_d16_hi v171, v103 offset:27056
	ds_write_b16 v171, v104 offset:27200
	ds_write_b16_d16_hi v171, v104 offset:27344
	ds_write_b16 v171, v105 offset:27488
	ds_write_b16_d16_hi v171, v105 offset:27632
	s_waitcnt vmcnt(0)
	ds_write_b16 v170, v106 offset:26624
	ds_write_b16_d16_hi v170, v106 offset:26768
	ds_write_b16 v170, v107 offset:26912
	ds_write_b16_d16_hi v170, v107 offset:27056
	ds_write_b16 v170, v108 offset:27200
	ds_write_b16_d16_hi v170, v108 offset:27344
	ds_write_b16 v170, v109 offset:27488
	ds_write_b16_d16_hi v170, v109 offset:27632
